# attention loop: dropped the 24-state s_nop pad before the row-max where 30+ instructions already separate it from the QK MFMAs
# baseline (speedup 1.0000x reference)
.LBB0_935:
	s_mul_hi_u32 s76, s93, 0xaaaaaaab
	s_lshr_b32 s76, s76, 1
	s_mul_i32 s76, s76, 0xd800
	v_subrev_u32_e32 v190, s76, v219
	v_subrev_u32_e32 v191, s76, v227
	s_waitcnt lgkmcnt(1)
	v_mfma_f32_32x32x16_bf16 v[96:111], v[164:167], v[156:159], v[96:111]
	ds_read_b128 v[172:175], v239 offset:26144
	ds_read_b128 v[164:167], v239 offset:17440
	ds_read_b128 v[240:243], v239 offset:17472
	ds_read_b128 v[168:171], v239 offset:26176
	v_exp_f32_e32 v64, v64
	v_exp_f32_e32 v80, v80
	v_exp_f32_e32 v65, v65
	v_exp_f32_e32 v81, v81
	v_exp_f32_e32 v66, v66
	s_waitcnt lgkmcnt(2)
	v_mfma_f32_32x32x16_bf16 v[96:111], v[164:167], v[152:155], v[96:111]
	v_exp_f32_e32 v82, v82
	v_exp_f32_e32 v67, v67
	v_exp_f32_e32 v83, v83
	v_add_f32_e32 v192, v64, v80
	v_exp_f32_e32 v68, v68
	v_exp_f32_e32 v84, v84
	v_add_f32_e32 v192, 0, v192
	v_mfma_f32_32x32x16_bf16 v[112:127], v[160:163], v[156:159], v[112:127]
	v_add_f32_e32 v193, v65, v81
	v_exp_f32_e32 v69, v69
	v_exp_f32_e32 v85, v85
	v_add_f32_e32 v192, v193, v192
	v_add_f32_e32 v193, v66, v82
	v_exp_f32_e32 v70, v70
	v_exp_f32_e32 v86, v86
	s_waitcnt lgkmcnt(1)
	v_mfma_f32_32x32x16_bf16 v[96:111], v[240:243], v[148:151], v[96:111]
	v_add_f32_e32 v192, v193, v192
	v_add_f32_e32 v193, v67, v83
	v_exp_f32_e32 v71, v71
	v_exp_f32_e32 v87, v87
	v_add_f32_e32 v192, v193, v192
	v_add_f32_e32 v193, v68, v84
	v_exp_f32_e32 v72, v72
	v_mfma_f32_32x32x16_bf16 v[112:127], v[172:175], v[152:155], v[112:127]
	v_exp_f32_e32 v88, v88
	v_add_f32_e32 v192, v193, v192
	v_add_f32_e32 v193, v69, v85
	v_exp_f32_e32 v73, v73
	v_exp_f32_e32 v89, v89
	ds_read_b128 v[244:247], v239 offset:17504
	ds_read_b128 v[164:167], v239 offset:26208
	v_add_f32_e32 v192, v193, v192
	v_add_f32_e32 v193, v70, v86
	v_exp_f32_e32 v74, v74
	v_exp_f32_e32 v90, v90
	v_add_f32_e32 v192, v193, v192
	v_add_f32_e32 v193, v71, v87
	v_exp_f32_e32 v75, v75
	v_exp_f32_e32 v91, v91
	v_add_f32_e32 v192, v193, v192
	v_add_f32_e32 v193, v72, v88
	v_exp_f32_e32 v76, v76
	v_exp_f32_e32 v92, v92
	v_add_f32_e32 v192, v193, v192
	v_add_f32_e32 v193, v73, v89
	v_exp_f32_e32 v77, v77
	v_exp_f32_e32 v93, v93
	s_waitcnt lgkmcnt(1)
	v_mfma_f32_32x32x16_bf16 v[96:111], v[244:247], v[144:147], v[96:111]
	v_add_f32_e32 v192, v193, v192
	v_add_f32_e32 v193, v74, v90
	v_exp_f32_e32 v78, v78
	v_exp_f32_e32 v94, v94
	v_add_f32_e32 v192, v193, v192
	v_add_f32_e32 v193, v75, v91
	v_exp_f32_e32 v79, v79
	v_mfma_f32_32x32x16_bf16 v[112:127], v[168:171], v[148:151], v[112:127]
	v_exp_f32_e32 v95, v95
	v_add_f32_e32 v192, v193, v192
	v_add_f32_e32 v193, v76, v92
	v_add_f32_e32 v192, v193, v192
	v_add_f32_e32 v193, v77, v93
	v_add_f32_e32 v192, v193, v192
	v_add_f32_e32 v193, v78, v94
	v_add_f32_e32 v192, v193, v192
	v_add_f32_e32 v193, v79, v95
	v_add_f32_e32 v192, v193, v192
	v_add_f32_e32 v169, v237, v192
	v_cvt_pk_bf16_f32 v64, v64, v65
	v_cvt_pk_bf16_f32 v65, v66, v67
	v_cvt_pk_bf16_f32 v66, v68, v69
	v_cvt_pk_bf16_f32 v67, v70, v71
	v_cvt_pk_bf16_f32 v68, v72, v73
	v_cvt_pk_bf16_f32 v69, v74, v75
	v_cvt_pk_bf16_f32 v70, v76, v77
	v_cvt_pk_bf16_f32 v71, v78, v79
	v_cvt_pk_bf16_f32 v72, v80, v81
	v_cvt_pk_bf16_f32 v73, v82, v83
	v_cvt_pk_bf16_f32 v74, v84, v85
	v_cvt_pk_bf16_f32 v75, v86, v87
	v_cvt_pk_bf16_f32 v76, v88, v89
	v_cvt_pk_bf16_f32 v77, v90, v91
	v_cvt_pk_bf16_f32 v78, v92, v93
	v_cvt_pk_bf16_f32 v79, v94, v95
	v_add_u32_e32 v168, s66, v222
	v_add_u32_e32 v84, v168, v190
	ds_read_b128 v[80:83], v84 offset:52224
	v_add_u32_e32 v85, v168, v191
	s_waitcnt lgkmcnt(1)
	v_mfma_f32_32x32x16_bf16 v[112:127], v[164:167], v[144:147], v[112:127]
	s_cmp_gt_u32 s64, 1
	s_waitcnt lgkmcnt(0)
	v_mfma_f32_32x32x16_bf16 v[0:15], v[64:67], v[80:83], v[0:15]
	ds_read_b128 v[80:83], v84 offset:56832
	s_waitcnt lgkmcnt(0)
	v_mfma_f32_32x32x16_bf16 v[16:31], v[64:67], v[80:83], v[16:31]
	ds_read_b128 v[80:83], v85
	s_waitcnt lgkmcnt(0)
	v_mfma_f32_32x32x16_bf16 v[32:47], v[64:67], v[80:83], v[32:47]
	ds_read_b128 v[80:83], v85 offset:4608
	s_waitcnt lgkmcnt(0)
	v_mfma_f32_32x32x16_bf16 v[48:63], v[64:67], v[80:83], v[48:63]
	ds_read_b128 v[64:67], v84 offset:52256
	s_waitcnt lgkmcnt(0)
	v_mfma_f32_32x32x16_bf16 v[0:15], v[68:71], v[64:67], v[0:15]
	ds_read_b128 v[64:67], v84 offset:56864
	s_waitcnt lgkmcnt(0)
	v_mfma_f32_32x32x16_bf16 v[16:31], v[68:71], v[64:67], v[16:31]
	ds_read_b128 v[64:67], v85 offset:32
	s_waitcnt lgkmcnt(0)
	v_mfma_f32_32x32x16_bf16 v[32:47], v[68:71], v[64:67], v[32:47]
	ds_read_b128 v[64:67], v85 offset:4640
	s_waitcnt lgkmcnt(0)
	v_mfma_f32_32x32x16_bf16 v[48:63], v[68:71], v[64:67], v[48:63]
	ds_read_b128 v[64:67], v84 offset:52288
	s_waitcnt lgkmcnt(0)
	v_mfma_f32_32x32x16_bf16 v[0:15], v[72:75], v[64:67], v[0:15]
	ds_read_b128 v[64:67], v84 offset:56896
	s_waitcnt lgkmcnt(0)
	v_mfma_f32_32x32x16_bf16 v[16:31], v[72:75], v[64:67], v[16:31]
	ds_read_b128 v[64:67], v85 offset:64
	s_waitcnt lgkmcnt(0)
	v_mfma_f32_32x32x16_bf16 v[32:47], v[72:75], v[64:67], v[32:47]
	ds_read_b128 v[64:67], v85 offset:4672
	s_waitcnt lgkmcnt(0)
	v_mfma_f32_32x32x16_bf16 v[48:63], v[72:75], v[64:67], v[48:63]
	ds_read_b128 v[64:67], v84 offset:52320
	ds_read_b128 v[68:71], v84 offset:56928
	ds_read_b128 v[72:75], v85 offset:96
	ds_read_b128 v[80:83], v85 offset:4704
	s_nop 0
	s_waitcnt lgkmcnt(3)
	v_mfma_f32_32x32x16_bf16 v[0:15], v[76:79], v[64:67], v[0:15]
	v_max3_f32 v64, v96, v112, v97
	v_max3_f32 v65, v113, v98, v114
	s_nop 0
	v_max3_f32 v64, v64, v99, v115
	v_max3_f32 v65, v65, v100, v116
	s_nop 0
	v_max3_f32 v64, v64, v101, v117
	s_waitcnt lgkmcnt(2)
	v_mfma_f32_32x32x16_bf16 v[16:31], v[76:79], v[68:71], v[16:31]
	v_max3_f32 v65, v65, v102, v118
	v_max3_f32 v64, v64, v103, v119
	s_nop 0
	v_max3_f32 v65, v65, v104, v120
	v_max3_f32 v64, v64, v105, v121
	s_nop 0
	v_max3_f32 v65, v65, v106, v122
	s_waitcnt lgkmcnt(1)
	v_mfma_f32_32x32x16_bf16 v[32:47], v[76:79], v[72:75], v[32:47]
	v_max3_f32 v64, v64, v107, v123
	v_max3_f32 v65, v65, v108, v124
	s_nop 0
	v_max3_f32 v64, v64, v109, v125
	v_max3_f32 v65, v65, v110, v126
	s_nop 0
	v_max3_f32 v64, v64, v111, v127
	s_waitcnt lgkmcnt(0)
	v_mfma_f32_32x32x16_bf16 v[48:63], v[76:79], v[80:83], v[48:63]
	v_max_f32_e32 v64, v64, v65
	s_nop 0
	v_mov_b32_e32 v65, v64
	s_nop 1
	v_permlane32_swap_b32_e32 v64, v65
	v_max_f32_e32 v64, v64, v65
	s_cbranch_scc1 .LBB0_937
	v_add_f32_e32 v65, v218, v64
	v_max_f32_e32 v66, v220, v220
	s_cmp_lg_u32 s33, -1
	v_max_f32_e32 v220, v66, v65
	s_cbranch_scc0 .LBB0_961

.LBB0_951:
	s_mul_i32 s67, s67, 0xd800
	v_subrev_u32_e32 v171, s67, v228
	v_subrev_u32_e32 v192, s67, v229
	v_subrev_u32_e32 v193, s67, v230
	v_subrev_u32_e32 v238, s67, v231
	v_subrev_u32_e32 v239, s67, v232
	v_subrev_u32_e32 v240, s67, v233
	v_subrev_u32_e32 v241, s67, v234
	v_subrev_u32_e32 v242, s67, v235
	v_subrev_u32_e32 v243, s67, v236
	v_exp_f32_e32 v244, v96
	v_exp_f32_e32 v245, v112
	v_exp_f32_e32 v176, v97
	v_exp_f32_e32 v112, v113
	v_exp_f32_e32 v246, v114
	v_add_f32_e32 v113, v245, v244
	v_exp_f32_e32 v114, v115
	v_pk_add_f32 v[96:97], v[112:113], v[176:177]
	v_exp_f32_e32 v113, v98
	v_pk_add_f32 v[172:173], v[96:97], v[96:97] op_sel_hi:[0,1]
	v_exp_f32_e32 v172, v99
	s_waitcnt lgkmcnt(1)
	v_mfma_f32_32x32x16_bf16 v[64:79], v[164:167], v[156:159], v[64:79]
	v_add_f32_e32 v115, v246, v113
	v_add_f32_e64 v96, v114, v172
	v_add_f32_e64 v97, v115, v173
	v_add_f32_e64 v174, v96, v96
	v_add_f32_e64 v175, v96, v97
	v_exp_f32_e32 v115, v100
	v_exp_f32_e32 v173, v116
	ds_read_b128 v[96:99], v170 offset:34848
	v_exp_f32_e32 v174, v101
	v_exp_f32_e32 v116, v117
	v_add_f32_e32 v117, v173, v115
	s_waitcnt lgkmcnt(1)
	v_mfma_f32_32x32x16_bf16 v[80:95], v[160:163], v[156:159], v[80:95]
	v_add_f32_e64 v100, v116, v174
	v_add_f32_e64 v101, v117, v175
	v_add_f32_e64 v164, v100, v100
	v_add_f32_e64 v165, v100, v101
	v_exp_f32_e32 v117, v102
	v_exp_f32_e32 v175, v118
	v_exp_f32_e32 v164, v103
	v_exp_f32_e32 v118, v119
	ds_read_b128 v[100:103], v170 offset:34880
	s_waitcnt lgkmcnt(1)
	v_mfma_f32_32x32x16_bf16 v[64:79], v[96:99], v[152:155], v[64:79]
	v_add_f32_e32 v119, v175, v117
	v_add_f32_e64 v96, v118, v164
	v_add_f32_e64 v97, v119, v165
	v_exp_f32_e32 v119, v104
	v_pk_add_f32 v[166:167], v[96:97], v[96:97] op_sel_hi:[0,1]
	v_exp_f32_e32 v165, v120
	v_exp_f32_e32 v166, v105
	v_exp_f32_e32 v120, v121
	ds_read_b128 v[96:99], v170 offset:34912
	v_add_f32_e32 v121, v165, v119
	s_waitcnt lgkmcnt(1)
	v_mfma_f32_32x32x16_bf16 v[64:79], v[100:103], v[148:151], v[64:79]
	v_add_f32_e64 v100, v120, v166
	v_add_f32_e64 v101, v121, v167
	v_exp_f32_e32 v121, v106
	v_pk_add_f32 v[190:191], v[100:101], v[100:101] op_sel_hi:[0,1]
	ds_read_b128 v[100:103], v170 offset:43552
	v_exp_f32_e32 v167, v122
	v_exp_f32_e32 v190, v107
	v_exp_f32_e32 v122, v123
	s_waitcnt lgkmcnt(1)
	v_mfma_f32_32x32x16_bf16 v[64:79], v[96:99], v[144:147], v[64:79]
	v_add_f32_e32 v123, v167, v121
	v_add_f32_e64 v96, v122, v190
	v_add_f32_e64 v97, v123, v191
	v_add_f32_e64 v106, v96, v96
	v_add_f32_e64 v107, v96, v97
	ds_read_b128 v[96:99], v170 offset:43584
	v_exp_f32_e32 v123, v108
	v_exp_f32_e32 v191, v124
	s_waitcnt lgkmcnt(1)
	v_mfma_f32_32x32x16_bf16 v[80:95], v[100:103], v[152:155], v[80:95]
	v_exp_f32_e32 v106, v109
	v_exp_f32_e32 v124, v125
	v_add_f32_e32 v125, v191, v123
	ds_read_b128 v[100:103], v170 offset:43616
	v_pk_add_f32 v[104:105], v[124:125], v[106:107]
	s_nop 0
	v_pk_add_f32 v[108:109], v[104:105], v[104:105] op_sel_hi:[0,1]
	v_exp_f32_e32 v107, v110
	v_exp_f32_e32 v125, v126
	s_waitcnt lgkmcnt(1)
	v_mfma_f32_32x32x16_bf16 v[80:95], v[96:99], v[148:151], v[80:95]
	v_exp_f32_e32 v108, v111
	v_exp_f32_e32 v126, v127
	v_add_f32_e32 v127, v125, v107
	v_pk_add_f32 v[104:105], v[126:127], v[108:109]
	s_nop 0
	v_add_f32_e32 v104, v104, v105
	v_add_f32_e32 v237, v169, v104
	v_cvt_pk_bf16_f32 v96, v244, v176
	v_cvt_pk_bf16_f32 v97, v113, v172
	v_cvt_pk_bf16_f32 v98, v115, v174
	v_cvt_pk_bf16_f32 v99, v117, v164
	v_cvt_pk_bf16_f32 v104, v119, v166
	v_cvt_pk_bf16_f32 v105, v121, v190
	v_cvt_pk_bf16_f32 v106, v123, v106
	v_cvt_pk_bf16_f32 v107, v107, v108
	v_cvt_pk_bf16_f32 v108, v245, v112
	v_cvt_pk_bf16_f32 v109, v246, v114
	v_cvt_pk_bf16_f32 v110, v173, v116
	v_cvt_pk_bf16_f32 v111, v175, v118
	v_cvt_pk_bf16_f32 v112, v165, v120
	v_cvt_pk_bf16_f32 v113, v167, v122
	v_cvt_pk_bf16_f32 v114, v191, v124
	v_cvt_pk_bf16_f32 v115, v125, v126
	v_add_u32_e32 v116, v168, v239
	ds_read_b128 v[116:119], v116
	s_waitcnt lgkmcnt(1)
	v_mfma_f32_32x32x16_bf16 v[80:95], v[100:103], v[144:147], v[80:95]
	s_waitcnt lgkmcnt(0)
	v_mfma_f32_32x32x16_bf16 v[0:15], v[96:99], v[116:119], v[0:15]
	v_add_u32_e32 v116, v168, v243
	ds_read_b128 v[116:119], v116
	s_waitcnt lgkmcnt(0)
	v_mfma_f32_32x32x16_bf16 v[16:31], v[96:99], v[116:119], v[16:31]
	v_add_u32_e32 v116, v168, v242
	ds_read_b128 v[100:103], v116
	s_waitcnt lgkmcnt(0)
	v_mfma_f32_32x32x16_bf16 v[32:47], v[96:99], v[100:103], v[32:47]
	ds_read_b128 v[100:103], v116 offset:4608
	s_waitcnt lgkmcnt(0)
	v_mfma_f32_32x32x16_bf16 v[48:63], v[96:99], v[100:103], v[48:63]
	v_add_u32_e32 v96, v168, v241
	ds_read_b128 v[96:99], v96
	s_waitcnt lgkmcnt(0)
	v_mfma_f32_32x32x16_bf16 v[0:15], v[104:107], v[96:99], v[0:15]
	v_add_u32_e32 v96, v168, v240
	ds_read_b128 v[96:99], v96
	s_waitcnt lgkmcnt(0)
	v_mfma_f32_32x32x16_bf16 v[16:31], v[104:107], v[96:99], v[16:31]
	ds_read_b128 v[96:99], v116 offset:32
	s_waitcnt lgkmcnt(0)
	v_mfma_f32_32x32x16_bf16 v[32:47], v[104:107], v[96:99], v[32:47]
	ds_read_b128 v[96:99], v116 offset:4640
	s_waitcnt lgkmcnt(0)
	v_mfma_f32_32x32x16_bf16 v[48:63], v[104:107], v[96:99], v[48:63]
	v_add_u32_e32 v96, v168, v238
	ds_read_b128 v[96:99], v96
	s_waitcnt lgkmcnt(0)
	v_mfma_f32_32x32x16_bf16 v[0:15], v[108:111], v[96:99], v[0:15]
	v_add_u32_e32 v96, v168, v193
	ds_read_b128 v[96:99], v96
	s_waitcnt lgkmcnt(0)
	v_mfma_f32_32x32x16_bf16 v[16:31], v[108:111], v[96:99], v[16:31]
	ds_read_b128 v[96:99], v116 offset:64
	s_waitcnt lgkmcnt(0)
	v_mfma_f32_32x32x16_bf16 v[32:47], v[108:111], v[96:99], v[32:47]
	ds_read_b128 v[96:99], v116 offset:4672
	ds_read_b128 v[100:103], v116 offset:96
	ds_read_b128 v[104:107], v116 offset:4704
	s_waitcnt lgkmcnt(2)
	v_mfma_f32_32x32x16_bf16 v[48:63], v[108:111], v[96:99], v[48:63]
	v_add_u32_e32 v96, v168, v192
	v_add_u32_e32 v108, v168, v171
	ds_read_b128 v[96:99], v96
	ds_read_b128 v[108:111], v108
	s_nop 0
	s_nop 0
	v_max3_f32 v116, v64, v80, v65
	v_max3_f32 v117, v81, v66, v82
	s_waitcnt lgkmcnt(1)
	v_mfma_f32_32x32x16_bf16 v[0:15], v[112:115], v[96:99], v[0:15]
	v_max3_f32 v96, v116, v67, v83
	v_max3_f32 v97, v117, v68, v84
	s_nop 0
	v_max3_f32 v96, v96, v69, v85
	v_max3_f32 v97, v97, v70, v86
	s_nop 0
	v_max3_f32 v96, v96, v71, v87
	v_max3_f32 v97, v97, v72, v88
	s_waitcnt lgkmcnt(0)
	v_mfma_f32_32x32x16_bf16 v[16:31], v[112:115], v[108:111], v[16:31]
	v_max3_f32 v96, v96, v73, v89
	v_max3_f32 v97, v97, v74, v90
	s_nop 0
	v_max3_f32 v96, v96, v75, v91
	v_max3_f32 v97, v97, v76, v92
	s_nop 0
	v_max3_f32 v96, v96, v77, v93
	v_mfma_f32_32x32x16_bf16 v[32:47], v[112:115], v[100:103], v[32:47]
	v_max3_f32 v97, v97, v78, v94
	v_max3_f32 v96, v96, v79, v95
	s_nop 0
	v_max_f32_e32 v96, v96, v97
	s_nop 0
	v_mov_b32_e32 v97, v96
	s_nop 1
	v_permlane32_swap_b32_e32 v96, v97
	v_mfma_f32_32x32x16_bf16 v[48:63], v[112:115], v[104:107], v[48:63]
	v_max_f32_e32 v96, v96, v97
	s_nop 0
	v_cmp_lt_f32_e32 vcc, s84, v96
	s_cmp_lg_u64 vcc, 0
	s_cselect_b64 s[74:75], -1, 0
	s_cbranch_vccz .LBB0_955
	v_max_f32_e32 v96, v96, v96
	v_max_f32_e32 v96, 0, v96
	v_exp_f32_e64 v97, -v96
	s_and_saveexec_b64 s[76:77], s[10:11]
	ds_write_b32 v214, v97
	s_or_b64 exec, exec, s[76:77]
	v_add_f32_e32 v218, v218, v96
	v_mul_f32_e32 v237, v237, v97
	v_sub_f32_e32 v79, v79, v96
	v_sub_f32_e32 v78, v78, v96
	v_sub_f32_e32 v77, v77, v96
	v_sub_f32_e32 v76, v76, v96
	v_sub_f32_e32 v75, v75, v96
	v_sub_f32_e32 v74, v74, v96
	v_sub_f32_e32 v73, v73, v96
	v_sub_f32_e32 v72, v72, v96
	v_sub_f32_e32 v71, v71, v96
	v_sub_f32_e32 v70, v70, v96
	v_sub_f32_e32 v69, v69, v96
	v_sub_f32_e32 v68, v68, v96
	v_sub_f32_e32 v67, v67, v96
	v_sub_f32_e32 v66, v66, v96
	v_sub_f32_e32 v65, v65, v96
	v_sub_f32_e32 v64, v64, v96
	v_sub_f32_e32 v95, v95, v96
	v_sub_f32_e32 v94, v94, v96
	v_sub_f32_e32 v93, v93, v96
	v_sub_f32_e32 v92, v92, v96
	v_sub_f32_e32 v91, v91, v96
	v_sub_f32_e32 v90, v90, v96
	v_sub_f32_e32 v89, v89, v96
	v_sub_f32_e32 v88, v88, v96
	v_sub_f32_e32 v87, v87, v96
	v_sub_f32_e32 v86, v86, v96
	v_sub_f32_e32 v85, v85, v96
	v_sub_f32_e32 v84, v84, v96
	v_sub_f32_e32 v83, v83, v96
	v_sub_f32_e32 v82, v82, v96
	v_sub_f32_e32 v81, v81, v96
	v_sub_f32_e32 v80, v80, v96

.LBB0_971:
	s_waitcnt lgkmcnt(1)
	v_mfma_f32_32x32x16_bf16 v[64:79], v[116:119], v[108:111], v[64:79]
	v_add_f32_e32 v129, v159, v162
	ds_read_b128 v[122:125], v120 offset:32
	ds_read_b128 v[190:193], v120 offset:64
	ds_read_b128 v[216:219], v120 offset:8736
	ds_read_b128 v[220:223], v120 offset:96
	ds_read_b128 v[224:227], v120 offset:8768
	ds_read_b128 v[228:231], v120 offset:8800
	v_pk_add_f32 v[116:117], v[128:129], v[176:177]
	v_add_f32_e32 v131, v160, v164
	v_pk_add_f32 v[116:117], v[116:117], v[116:117] op_sel_hi:[0,1]
	v_mov_b32_e32 v139, v117
	v_pk_add_f32 v[116:117], v[130:131], v[138:139]
	s_waitcnt lgkmcnt(5)
	v_mfma_f32_32x32x16_bf16 v[64:79], v[122:125], v[104:107], v[64:79]
	v_pk_add_f32 v[116:117], v[116:117], v[116:117] op_sel_hi:[0,1]
	v_add_f32_e32 v133, v161, v166
	v_mov_b32_e32 v141, v117
	v_pk_add_f32 v[116:117], v[132:133], v[140:141]
	v_add_f32_e32 v135, v163, v168
	v_pk_add_f32 v[116:117], v[116:117], v[116:117] op_sel_hi:[0,1]
	v_mov_b32_e32 v145, v117
	v_mfma_f32_32x32x16_bf16 v[80:95], v[112:115], v[108:111], v[80:95]
	v_add_f32_e64 v116, v134, v144
	v_add_f32_e64 v117, v135, v145
	v_add_f32_e32 v137, v165, v170
	v_pk_add_f32 v[116:117], v[116:117], v[116:117] op_sel_hi:[0,1]
	v_mov_b32_e32 v149, v117
	v_pk_add_f32 v[116:117], v[136:137], v[148:149]
	v_add_f32_e32 v143, v167, v172
	v_pk_add_f32 v[116:117], v[116:117], v[116:117] op_sel_hi:[0,1]
	s_waitcnt lgkmcnt(4)
	v_mfma_f32_32x32x16_bf16 v[64:79], v[190:193], v[100:103], v[64:79]
	v_mov_b32_e32 v153, v117
	v_add_f32_e64 v116, v142, v152
	v_add_f32_e64 v117, v143, v153
	v_add_f32_e32 v147, v169, v173
	v_pk_add_f32 v[116:117], v[116:117], v[116:117] op_sel_hi:[0,1]
	v_mov_b32_e32 v155, v117
	v_pk_add_f32 v[116:117], v[146:147], v[154:155]
	v_add_f32_e32 v151, v171, v174
	s_waitcnt lgkmcnt(3)
	v_mfma_f32_32x32x16_bf16 v[80:95], v[216:219], v[104:107], v[80:95]
	v_pk_add_f32 v[116:117], v[116:117], v[116:117] op_sel_hi:[0,1]
	v_mov_b32_e32 v157, v117
	v_pk_add_f32 v[108:109], v[150:151], v[156:157]
	s_nop 0
	v_add_f32_e32 v108, v108, v109
	v_add_f32_e32 v108, v237, v108
	s_waitcnt lgkmcnt(2)
	v_mfma_f32_32x32x16_bf16 v[64:79], v[220:223], v[96:99], v[64:79]
	v_cvt_pk_bf16_f32 v110, v162, v176
	v_cvt_pk_bf16_f32 v111, v164, v138
	v_cvt_pk_bf16_f32 v112, v166, v140
	v_cvt_pk_bf16_f32 v113, v168, v144
	v_cvt_pk_bf16_f32 v104, v170, v148
	v_cvt_pk_bf16_f32 v105, v172, v152
	v_cvt_pk_bf16_f32 v106, v173, v154
	s_waitcnt lgkmcnt(1)
	v_mfma_f32_32x32x16_bf16 v[80:95], v[224:227], v[100:103], v[80:95]
	v_cvt_pk_bf16_f32 v107, v174, v156
	v_cvt_pk_bf16_f32 v114, v159, v128
	v_cvt_pk_bf16_f32 v115, v160, v130
	v_cvt_pk_bf16_f32 v116, v161, v132
	v_cvt_pk_bf16_f32 v117, v163, v134
	v_cvt_pk_bf16_f32 v100, v165, v136
	v_cvt_pk_bf16_f32 v101, v167, v142
	v_cvt_pk_bf16_f32 v102, v169, v146
	v_cvt_pk_bf16_f32 v103, v171, v150
	s_add_i32 s64, s64, 1
	s_mul_hi_u32 s0, s64, 0xaaaaaaab
	s_lshr_b32 s0, s0, 1
	s_mul_i32 s0, s0, 3
	s_sub_i32 s0, s64, s0
	s_mulk_i32 s0, 0x4800
	v_add_u32_e32 v109, s0, v158
	ds_read_b128 v[118:121], v109 offset:52224
	ds_read_b128 v[122:125], v109 offset:52256
	s_waitcnt lgkmcnt(2)
	v_mfma_f32_32x32x16_bf16 v[80:95], v[228:231], v[96:99], v[80:95]
	v_add_u32_e32 v134, 0xcc00, v109
	s_waitcnt lgkmcnt(1)
	v_mfma_f32_32x32x16_bf16 v[0:15], v[110:113], v[118:121], v[0:15]
	ds_read_b128 v[118:121], v109 offset:56832
	ds_read_b128 v[126:129], v109 offset:56864
	s_waitcnt lgkmcnt(1)
	v_mfma_f32_32x32x16_bf16 v[16:31], v[110:113], v[118:121], v[16:31]
	ds_read_b128 v[96:99], v109 offset:61440
	ds_read_b128 v[118:121], v109 offset:61472
	s_waitcnt lgkmcnt(1)
	v_mfma_f32_32x32x16_bf16 v[32:47], v[110:113], v[96:99], v[32:47]
	ds_read_b128 v[96:99], v134 offset:13824
	ds_read_b128 v[130:133], v134 offset:13856
	s_waitcnt lgkmcnt(1)
	v_mfma_f32_32x32x16_bf16 v[48:63], v[110:113], v[96:99], v[48:63]
	v_mfma_f32_32x32x16_bf16 v[0:15], v[104:107], v[122:125], v[0:15]
	v_mfma_f32_32x32x16_bf16 v[16:31], v[104:107], v[126:129], v[16:31]
	v_mfma_f32_32x32x16_bf16 v[32:47], v[104:107], v[118:121], v[32:47]
	s_waitcnt lgkmcnt(0)
	v_mfma_f32_32x32x16_bf16 v[48:63], v[104:107], v[130:133], v[48:63]
	ds_read_b128 v[96:99], v109 offset:52288
	ds_read_b128 v[104:107], v109 offset:52320
	s_waitcnt lgkmcnt(1)
	v_mfma_f32_32x32x16_bf16 v[0:15], v[114:117], v[96:99], v[0:15]
	ds_read_b128 v[96:99], v109 offset:56896
	ds_read_b128 v[110:113], v109 offset:56928
	s_waitcnt lgkmcnt(1)
	v_mfma_f32_32x32x16_bf16 v[16:31], v[114:117], v[96:99], v[16:31]
	ds_read_b128 v[96:99], v109 offset:61504
	ds_read_b128 v[118:121], v109 offset:61536
	s_waitcnt lgkmcnt(1)
	v_mfma_f32_32x32x16_bf16 v[32:47], v[114:117], v[96:99], v[32:47]
	ds_read_b128 v[96:99], v134 offset:13888
	ds_read_b128 v[122:125], v134 offset:13920
	s_nop 0
	s_waitcnt lgkmcnt(1)
	v_mfma_f32_32x32x16_bf16 v[48:63], v[114:117], v[96:99], v[48:63]
	v_max3_f32 v96, v64, v80, v65
	v_max3_f32 v97, v81, v66, v82
	s_nop 0
	v_max3_f32 v96, v96, v67, v83
	v_max3_f32 v97, v97, v68, v84
	s_nop 0
	v_max3_f32 v96, v96, v69, v85
	v_max3_f32 v97, v97, v70, v86
	v_mfma_f32_32x32x16_bf16 v[0:15], v[100:103], v[104:107], v[0:15]
	v_max3_f32 v96, v96, v71, v87
	v_max3_f32 v97, v97, v72, v88
	s_nop 0
	v_max3_f32 v96, v96, v73, v89
	v_max3_f32 v97, v97, v74, v90
	s_nop 0
	v_max3_f32 v96, v96, v75, v91
	v_mfma_f32_32x32x16_bf16 v[16:31], v[100:103], v[110:113], v[16:31]
	v_max3_f32 v97, v97, v76, v92
	v_max3_f32 v96, v96, v77, v93
	s_nop 0
	v_max3_f32 v97, v97, v78, v94
	v_max3_f32 v96, v96, v79, v95
	s_nop 0
	v_max_f32_e32 v96, v96, v97
	v_mfma_f32_32x32x16_bf16 v[32:47], v[100:103], v[118:121], v[32:47]
	v_mov_b32_e32 v97, v96
	s_nop 1
	v_permlane32_swap_b32_e32 v96, v97
	v_max_f32_e32 v96, v96, v97
	s_nop 0
	v_cmp_lt_f32_e32 vcc, s84, v96
	s_cmp_lg_u64 vcc, 0
	s_waitcnt lgkmcnt(0)
	v_mfma_f32_32x32x16_bf16 v[48:63], v[100:103], v[122:125], v[48:63]
	s_cselect_b64 s[12:13], -1, 0
	s_cbranch_vccz .LBB0_975
	v_max_f32_e32 v96, v96, v96
	v_max_f32_e32 v96, 0, v96
	v_exp_f32_e64 v97, -v96
	s_and_saveexec_b64 s[16:17], s[10:11]
	ds_write_b32 v214, v97
	s_or_b64 exec, exec, s[16:17]
	v_mul_f32_e32 v108, v108, v97
	v_sub_f32_e32 v79, v79, v96
	v_sub_f32_e32 v78, v78, v96
	v_sub_f32_e32 v77, v77, v96
	v_sub_f32_e32 v76, v76, v96
	v_sub_f32_e32 v75, v75, v96
	v_sub_f32_e32 v74, v74, v96
	v_sub_f32_e32 v73, v73, v96
	v_sub_f32_e32 v72, v72, v96
	v_sub_f32_e32 v71, v71, v96
	v_sub_f32_e32 v70, v70, v96
	v_sub_f32_e32 v69, v69, v96
	v_sub_f32_e32 v68, v68, v96
	v_sub_f32_e32 v67, v67, v96
	v_sub_f32_e32 v66, v66, v96
	v_sub_f32_e32 v65, v65, v96
	v_sub_f32_e32 v64, v64, v96
	v_sub_f32_e32 v95, v95, v96
	v_sub_f32_e32 v94, v94, v96
	v_sub_f32_e32 v93, v93, v96
	v_sub_f32_e32 v92, v92, v96
	v_sub_f32_e32 v91, v91, v96
	v_sub_f32_e32 v90, v90, v96
	v_sub_f32_e32 v89, v89, v96
	v_sub_f32_e32 v88, v88, v96
	v_sub_f32_e32 v87, v87, v96
	v_sub_f32_e32 v86, v86, v96
	v_sub_f32_e32 v85, v85, v96
	v_sub_f32_e32 v84, v84, v96
	v_sub_f32_e32 v83, v83, v96
	v_sub_f32_e32 v82, v82, v96
	v_sub_f32_e32 v81, v81, v96
	v_sub_f32_e32 v80, v80, v96
